# GLA scan loop: counted vmcnt(10/9/8) instead of vmcnt(1/0/3) at loop head, peeled vmcnt(0) into preheader
# speedup vs baseline: 1.0066x; 1.0066x over previous
.LBB0_865:
	s_mov_b64 s[82:83], 0
	s_and_b64 vcc, exec, s[6:7]
	s_mov_b64 s[6:7], 0
	s_cbranch_vccz .LBB0_879
	s_lshl_b64 s[96:97], s[56:57], 15
	s_add_u32 s3, s42, s96
	s_addc_u32 s8, s43, s97
	s_and_b64 s[6:7], s[80:81], exec
	s_cselect_b32 vcc_hi, s8, 0
	s_cselect_b32 vcc_lo, s3, 0
	s_lshl_b32 s3, s59, 7
	v_readlane_b32 s6, v254, 42
	s_add_u32 s6, s6, s3
	v_readlane_b32 s7, v254, 43
	s_addc_u32 s7, s7, 0
	v_readlane_b32 s8, v254, 44
	s_add_u32 s8, s8, s3
	v_readlane_b32 s9, v254, 45
	s_addc_u32 s9, s9, 0
	s_lshl_b32 s14, s59, 8
	v_readlane_b32 s10, v254, 38
	s_add_u32 s10, s10, s14
	v_readlane_b32 s11, v254, 39
	s_addc_u32 s11, s11, 0
	s_lshl_b32 s12, s58, 9
	v_readlane_b32 s13, v254, 50
	s_add_u32 s12, s13, s12
	v_readlane_b32 s13, v254, 51
	s_addc_u32 s13, s13, 0
	s_add_u32 s12, s12, s3
	s_addc_u32 s13, s13, 0
	s_add_u32 s80, s28, s14
	s_addc_u32 s81, s76, 0
	s_lshr_b32 s3, s74, 5
	v_mov_b32_e32 v1, v224
	s_cmp_eq_u64 vcc, 0
	s_cselect_b64 s[14:15], -1, 0
	v_ashrrev_i32_e32 v3, 6, v1
	v_and_b32_e32 v126, 15, v1
	v_lshlrev_b32_e32 v0, 4, v3
	s_waitcnt vmcnt(2)
	v_lshrrev_b32_e32 v4, 2, v1
	s_and_b64 s[16:17], s[14:15], exec
	v_and_b32_e32 v5, 8, v4
	v_or_b32_e32 v88, v0, v126
	v_and_b32_e32 v57, 12, v4
	v_lshlrev_b32_e32 v4, 4, v1
	s_cselect_b32 s16, s41, vcc_hi
	s_cselect_b32 s17, s40, vcc_lo
	v_and_or_b32 v56, v0, 48, v5
	v_ashrrev_i32_e32 v89, 31, v88
	v_lshlrev_b32_e32 v96, 9, v57
	v_and_b32_e32 v54, 0xf0, v4
	v_mov_b32_e32 v4, s17
	v_mov_b32_e32 v5, s16
	v_or_b32_e32 v108, 0x6000, v96
	v_mov_b32_e32 v109, v2
	v_or_b32_e32 v110, 0x6200, v96
	v_mov_b32_e32 v111, v2
	v_or_b32_e32 v112, 0x6400, v96
	v_mov_b32_e32 v113, v2
	v_or_b32_e32 v114, 0x6600, v96
	v_mov_b32_e32 v115, v2
	v_lshl_add_u64 v[4:5], v[88:89], 2, v[4:5]
	v_mov_b32_e32 v97, v2
	v_or_b32_e32 v90, 0x2000, v96
	v_mov_b32_e32 v91, v2
	v_or_b32_e32 v92, 0x2200, v96
	v_mov_b32_e32 v93, v2
	v_or_b32_e32 v94, 0x2400, v96
	v_mov_b32_e32 v95, v2
	v_or_b32_e32 v98, 0x2600, v96
	v_mov_b32_e32 v99, v2
	v_or_b32_e32 v100, 0x4000, v96
	v_mov_b32_e32 v101, v2
	v_or_b32_e32 v102, 0x4200, v96
	v_mov_b32_e32 v103, v2
	v_or_b32_e32 v104, 0x4400, v96
	v_mov_b32_e32 v105, v2
	v_or_b32_e32 v106, 0x4600, v96
	v_mov_b32_e32 v107, v2
	v_lshl_add_u64 v[6:7], v[4:5], 0, v[108:109]
	v_lshl_add_u64 v[8:9], v[4:5], 0, v[110:111]
	v_lshl_add_u64 v[10:11], v[4:5], 0, v[112:113]
	v_lshl_add_u64 v[12:13], v[4:5], 0, v[114:115]
	v_ashrrev_i32_e32 v128, 4, v1
	v_lshl_add_u64 v[14:15], v[4:5], 0, v[100:101]
	v_lshl_add_u64 v[16:17], v[4:5], 0, v[102:103]
	v_lshl_add_u64 v[18:19], v[4:5], 0, v[104:105]
	v_lshl_add_u64 v[20:21], v[4:5], 0, v[106:107]
	global_load_dword v36, v[6:7], off
	global_load_dword v37, v[8:9], off
	global_load_dword v38, v[10:11], off
	global_load_dword v39, v[12:13], off
	global_load_dword v40, v[14:15], off
	global_load_dword v41, v[16:17], off
	global_load_dword v42, v[18:19], off
	global_load_dword v43, v[20:21], off
	v_lshl_add_u64 v[6:7], v[4:5], 0, v[90:91]
	v_lshl_add_u64 v[8:9], v[4:5], 0, v[92:93]
	v_lshl_add_u64 v[10:11], v[4:5], 0, v[94:95]
	v_lshl_add_u64 v[12:13], v[4:5], 0, v[98:99]
	v_lshl_add_u64 v[4:5], v[4:5], 0, v[96:97]
	global_load_dword v44, v[6:7], off
	global_load_dword v45, v[8:9], off
	global_load_dword v46, v[10:11], off
	global_load_dword v47, v[12:13], off
	global_load_dword v48, v[4:5], off
	global_load_dword v49, v[4:5], off offset:512
	global_load_dword v50, v[4:5], off offset:1024
	global_load_dword v51, v[4:5], off offset:1536
	v_sub_u32_e32 v5, s74, v128
	v_add_u32_e32 v4, 32, v128
	v_subrev_u32_e32 v5, 33, v5
	v_cndmask_b32_e64 v4, v5, v4, s[4:5]
	v_add_u32_e32 v4, s73, v4
	v_mov_b64_e32 v[8:9], s[10:11]
	v_mad_i64_i32 v[4:5], s[16:17], v4, s89, v[8:9]
	s_movk_i32 s16, 0xffdf
	v_and_b32_e32 v127, 31, v1
	v_bitop3_b32 v7, v1, s16, 31 bitop3:0x6c
	v_or_b32_e32 v6, 32, v127
	v_add_u32_e32 v7, s74, v7
	v_cndmask_b32_e64 v6, v7, v6, s[4:5]
	v_add_u32_e32 v10, s73, v6
	v_ashrrev_i32_e32 v11, 31, v10
	v_mov_b64_e32 v[16:17], s[8:9]
	v_lshlrev_b64 v[18:19], 10, v[10:11]
	v_mov_b64_e32 v[24:25], s[6:7]
	v_lshlrev_b32_e32 v52, 1, v56
	v_mov_b32_e32 v53, v2
	v_mov_b32_e32 v55, v2
	v_mad_i64_i32 v[6:7], s[16:17], v10, s89, v[16:17]
	v_lshl_add_u64 v[18:19], s[12:13], 0, v[18:19]
	v_mad_i64_i32 v[10:11], s[16:17], v10, s89, v[24:25]
	v_lshl_add_u64 v[4:5], v[4:5], 0, v[54:55]
	v_lshl_add_u64 v[12:13], v[6:7], 0, v[52:53]
	v_lshl_add_u64 v[18:19], v[18:19], 0, v[52:53]
	v_lshl_add_u64 v[10:11], v[10:11], 0, v[52:53]
	global_load_dwordx4 v[4:7], v[4:5], off
	s_nop 0
	global_load_dwordx4 v[12:15], v[12:13], off
	s_nop 0
	global_load_dwordx4 v[28:31], v[18:19], off
	global_load_dwordx4 v[20:23], v[10:11], off
	v_xad_u32 v10, v128, -1, s74
	v_cndmask_b32_e64 v10, v10, v128, s[4:5]
	v_add_u32_e32 v10, s73, v10
	v_mad_i64_i32 v[8:9], s[16:17], v10, s89, v[8:9]
	v_xad_u32 v10, v127, -1, s74
	v_cndmask_b32_e64 v10, v10, v127, s[4:5]
	v_add_u32_e32 v26, s73, v10
	v_ashrrev_i32_e32 v27, 31, v26
	v_lshlrev_b64 v[32:33], 10, v[26:27]
	v_mad_i64_i32 v[10:11], s[16:17], v26, s89, v[16:17]
	v_lshl_add_u64 v[32:33], s[12:13], 0, v[32:33]
	v_mad_i64_i32 v[24:25], s[16:17], v26, s89, v[24:25]
	v_lshl_add_u64 v[8:9], v[8:9], 0, v[54:55]
	v_lshl_add_u64 v[16:17], v[10:11], 0, v[52:53]
	v_lshl_add_u64 v[32:33], v[32:33], 0, v[52:53]
	v_lshl_add_u64 v[24:25], v[24:25], 0, v[52:53]
	global_load_dwordx4 v[8:11], v[8:9], off
	s_nop 0
	global_load_dwordx4 v[16:19], v[16:17], off
	s_nop 0
	global_load_dwordx4 v[32:35], v[32:33], off
	s_nop 0
	global_load_dwordx4 v[24:27], v[24:25], off
	v_lshlrev_b32_e32 v58, 3, v1
	v_lshl_add_u64 v[116:117], s[6:7], 0, v[52:53]
	v_lshl_add_u64 v[122:123], s[10:11], 0, v[54:55]
	v_lshlrev_b32_e32 v55, 2, v56
	v_lshlrev_b32_e32 v56, 2, v1
	s_movk_i32 s6, 0xfc
	v_and_or_b32 v129, v56, s71, 60
	v_bitop3_b32 v130, v56, s6, v188 bitop3:0xc8
	v_bitop3_b32 v56, v58, s71, v58 bitop3:0xc
	v_lshl_add_u64 v[118:119], s[12:13], 0, v[52:53]
	v_lshl_add_u64 v[120:121], s[8:9], 0, v[52:53]
	v_add_u32_e32 v53, 0, v52
	v_lshlrev_b32_e32 v56, 2, v56
	v_add3_u32 v131, v53, v52, v56
	v_mul_u32_u24_e32 v52, 0x48, v127
	v_lshl_add_u32 v132, v52, 1, v53
	s_movk_i32 s8, 0x110
	v_bfe_u32 v53, v1, 2, 4
	v_mul_lo_u32 v52, v128, s8
	v_mul_u32_u24_e32 v1, 0x88, v53
	v_cmp_gt_i32_e32 vcc, 4, v3
	v_add3_u32 v133, 0, v54, v52
	v_lshl_add_u32 v52, v1, 1, 0
	v_lshlrev_b32_e32 v3, 5, v3
	v_and_b32_e32 v54, 24, v58
	v_add3_u32 v134, v52, v3, v54
	v_lshlrev_b32_e32 v52, 1, v57
	v_mul_u32_u24_e32 v58, 0x48, v126
	v_ashrrev_i32_e32 v1, 31, v0
	v_add_u32_e32 v3, 0, v52
	v_lshlrev_b32_e32 v58, 1, v58
	v_add_u32_e32 v135, v3, v58
	v_add3_u32 v136, 0, v58, v52
	v_or_b32_e32 v58, 2, v57
	v_add_u32_e32 v137, v3, v52
	v_mul_u32_u24_e32 v3, 0x48, v53
	v_lshl_add_u64 v[0:1], v[0:1], 1, s[80:81]
	v_mov_b32_e32 v53, v2
	v_cmp_gt_u32_e64 s[12:13], v58, v126
	v_or_b32_e32 v58, 3, v57
	v_lshlrev_b32_e32 v3, 1, v3
	v_lshl_add_u64 v[124:125], v[0:1], 0, v[52:53]
	v_lshlrev_b32_e32 v0, 2, v57
	s_mov_b32 s35, 3
	s_waitcnt vmcnt(23)
	v_cndmask_b32_e64 v36, v36, 0, s[14:15]
	s_waitcnt vmcnt(22)
	v_cndmask_b32_e64 v37, v37, 0, s[14:15]
	s_waitcnt vmcnt(21)
	v_cndmask_b32_e64 v38, v38, 0, s[14:15]
	s_waitcnt vmcnt(20)
	v_cndmask_b32_e64 v39, v39, 0, s[14:15]
	s_waitcnt vmcnt(19)
	v_cndmask_b32_e64 v40, v40, 0, s[14:15]
	s_waitcnt vmcnt(18)
	v_cndmask_b32_e64 v41, v41, 0, s[14:15]
	s_waitcnt vmcnt(17)
	v_cndmask_b32_e64 v42, v42, 0, s[14:15]
	s_waitcnt vmcnt(16)
	v_cndmask_b32_e64 v43, v43, 0, s[14:15]
	s_waitcnt vmcnt(15)
	v_cndmask_b32_e64 v44, v44, 0, s[14:15]
	s_waitcnt vmcnt(14)
	v_cndmask_b32_e64 v45, v45, 0, s[14:15]
	s_waitcnt vmcnt(13)
	v_cndmask_b32_e64 v46, v46, 0, s[14:15]
	s_waitcnt vmcnt(12)
	v_cndmask_b32_e64 v47, v47, 0, s[14:15]
	s_waitcnt vmcnt(11)
	v_cndmask_b32_e64 v48, v48, 0, s[14:15]
	s_waitcnt vmcnt(10)
	v_cndmask_b32_e64 v49, v49, 0, s[14:15]
	s_waitcnt vmcnt(9)
	v_cndmask_b32_e64 v50, v50, 0, s[14:15]
	s_waitcnt vmcnt(8)
	v_cndmask_b32_e64 v51, v51, 0, s[14:15]
	v_cmp_eq_u32_e64 s[6:7], 15, v126
	s_add_i32 s77, s3, -1
	v_cmp_gt_u32_e64 s[8:9], v57, v126
	v_cmp_lt_u32_e64 s[10:11], v57, v126
	v_cmp_gt_u32_e64 s[14:15], v58, v126
	v_add3_u32 v138, 0, v3, v54
	v_add3_u32 v139, s88, v55, v56
	v_add_u32_e32 v140, 0xf200, v134
	v_add_u32_e32 v141, s72, v0
	v_add_u32_e32 v142, s75, v0
	v_add_u32_e32 v143, s18, v0
	v_add_u32_e32 v144, s19, v0
	v_add_u32_e32 v145, s88, v0
	v_add_u32_e32 v146, s70, v0
	v_add_u32_e32 v147, s29, v0
	v_add_u32_e32 v148, s68, v0
	v_xad_u32 v149, v126, -1, s74
	s_waitcnt vmcnt(0)
	s_branch .LBB0_869
.LBB0_867:
	s_or_b64 exec, exec, s[16:17]
	s_waitcnt vmcnt(9)
	v_rcp_f32_e32 v66, v28
	v_rcp_f32_e32 v67, v29
	v_lshlrev_b32_e32 v62, 16, v20
	v_and_b32_e32 v63, 0xffff0000, v20
	v_pk_mul_f32 v[28:29], v[28:29], v[62:63]
	v_lshlrev_b32_e32 v62, 16, v12
	v_and_b32_e32 v63, 0xffff0000, v12
	v_pk_mul_f32 v[62:63], v[66:67], v[62:63]
	v_rcp_f32_e32 v66, v30
	v_rcp_f32_e32 v67, v31
	v_lshlrev_b32_e32 v20, 16, v21
	v_and_b32_e32 v21, 0xffff0000, v21
	v_lshlrev_b32_e32 v12, 16, v13
	v_and_b32_e32 v13, 0xffff0000, v13
	v_pk_mul_f32 v[20:21], v[30:31], v[20:21]
	v_pk_mul_f32 v[30:31], v[66:67], v[12:13]
	v_rcp_f32_e32 v12, v54
	v_rcp_f32_e32 v13, v55
	v_lshlrev_b32_e32 v64, 16, v22
	v_and_b32_e32 v65, 0xffff0000, v22
	v_pk_mul_f32 v[54:55], v[54:55], v[64:65]
	v_lshlrev_b32_e32 v64, 16, v14
	v_and_b32_e32 v65, 0xffff0000, v14
	v_pk_mul_f32 v[64:65], v[12:13], v[64:65]
	v_rcp_f32_e32 v12, v58
	v_rcp_f32_e32 v13, v59
	v_lshlrev_b32_e32 v22, 16, v23
	v_and_b32_e32 v23, 0xffff0000, v23
	v_pk_mul_f32 v[22:23], v[58:59], v[22:23]
	v_lshlrev_b32_e32 v14, 16, v15
	v_and_b32_e32 v15, 0xffff0000, v15
	v_pk_mul_f32 v[58:59], v[12:13], v[14:15]
	v_cvt_pk_bf16_f32 v12, v28, v29
	v_cvt_pk_bf16_f32 v13, v20, v21
	v_cvt_pk_bf16_f32 v14, v54, v55
	v_cvt_pk_bf16_f32 v15, v22, v23
	s_waitcnt lgkmcnt(6)
	v_pk_mul_f32 v[0:1], v[62:63], v[0:1]
	s_waitcnt lgkmcnt(4)
	v_pk_mul_f32 v[52:53], v[30:31], v[52:53]
	s_waitcnt lgkmcnt(2)
	v_pk_mul_f32 v[60:61], v[64:65], v[60:61]
	s_waitcnt lgkmcnt(0)
	v_pk_mul_f32 v[56:57], v[58:59], v[56:57]
	ds_write_b128 v132, v[12:15] offset:35840
	v_cvt_pk_bf16_f32 v12, v62, v63
	v_cvt_pk_bf16_f32 v13, v30, v31
	v_cvt_pk_bf16_f32 v14, v64, v65
	v_cvt_pk_bf16_f32 v15, v58, v59
	ds_write_b128 v132, v[12:15] offset:44544
	v_cvt_pk_bf16_f32 v12, v0, v1
	v_cvt_pk_bf16_f32 v13, v52, v53
	v_cvt_pk_bf16_f32 v14, v60, v61
	v_cvt_pk_bf16_f32 v15, v56, v57
	ds_write_b128 v132, v[12:15] offset:53248

.LBB0_869:
	s_and_saveexec_b64 s[80:81], vcc
	s_cbranch_execz .LBB0_873
	s_waitcnt vmcnt(10)
	v_cvt_f32_f16_e32 v0, v32
	v_cvt_f32_f16_sdwa v1, v32 dst_sel:DWORD dst_unused:UNUSED_PAD src0_sel:WORD_1
	v_cvt_f32_f16_e32 v3, v33
	v_cvt_f32_f16_sdwa v32, v33 dst_sel:DWORD dst_unused:UNUSED_PAD src0_sel:WORD_1
	v_add_f32_dpp v0, v0, v0 row_shr:1 row_mask:0xf bank_mask:0xf bound_ctrl:1
	v_add_f32_dpp v1, v1, v1 row_shr:1 row_mask:0xf bank_mask:0xf bound_ctrl:1
	v_mov_b32_e32 v53, v2
	v_add_f32_dpp v0, v0, v0 row_shr:2 row_mask:0xf bank_mask:0xf bound_ctrl:1
	v_add_f32_dpp v1, v1, v1 row_shr:2 row_mask:0xf bank_mask:0xf bound_ctrl:1
	v_cvt_f32_f16_e32 v33, v34
	v_add_f32_dpp v0, v0, v0 row_shr:4 row_mask:0xf bank_mask:0xf bound_ctrl:1
	v_add_f32_dpp v3, v3, v3 row_shr:1 row_mask:0xf bank_mask:0xf bound_ctrl:1
	v_add_f32_dpp v1, v1, v1 row_shr:4 row_mask:0xf bank_mask:0xf bound_ctrl:1
	v_add_f32_dpp v0, v0, v0 row_shr:8 row_mask:0xf bank_mask:0xf bound_ctrl:1
	v_add_f32_dpp v3, v3, v3 row_shr:2 row_mask:0xf bank_mask:0xf bound_ctrl:1
	v_add_f32_dpp v1, v1, v1 row_shr:8 row_mask:0xf bank_mask:0xf bound_ctrl:1
	v_mov_b32_dpp v53, v0 row_bcast:15 row_mask:0xa bank_mask:0xf
	v_add_f32_e32 v62, v0, v53
	v_mov_b32_e32 v0, v2
	v_cvt_f32_f16_sdwa v34, v34 dst_sel:DWORD dst_unused:UNUSED_PAD src0_sel:WORD_1
	v_add_f32_dpp v32, v32, v32 row_shr:1 row_mask:0xf bank_mask:0xf bound_ctrl:1
	v_add_f32_dpp v3, v3, v3 row_shr:4 row_mask:0xf bank_mask:0xf bound_ctrl:1
	v_mov_b32_dpp v0, v1 row_bcast:15 row_mask:0xa bank_mask:0xf
	v_add_f32_dpp v32, v32, v32 row_shr:2 row_mask:0xf bank_mask:0xf bound_ctrl:1
	v_add_f32_dpp v3, v3, v3 row_shr:8 row_mask:0xf bank_mask:0xf bound_ctrl:1
	v_add_f32_e32 v63, v1, v0
	v_mov_b32_e32 v0, v2
	v_cvt_f32_f16_e32 v52, v35
	v_add_f32_dpp v33, v33, v33 row_shr:1 row_mask:0xf bank_mask:0xf bound_ctrl:1
	v_add_f32_dpp v32, v32, v32 row_shr:4 row_mask:0xf bank_mask:0xf bound_ctrl:1
	v_mov_b32_dpp v0, v3 row_bcast:15 row_mask:0xa bank_mask:0xf
	v_add_f32_dpp v33, v33, v33 row_shr:2 row_mask:0xf bank_mask:0xf bound_ctrl:1
	v_add_f32_dpp v32, v32, v32 row_shr:8 row_mask:0xf bank_mask:0xf bound_ctrl:1
	v_add_f32_e32 v64, v3, v0
	v_mov_b32_e32 v0, v2
	v_add_f32_dpp v34, v34, v34 row_shr:1 row_mask:0xf bank_mask:0xf bound_ctrl:1
	v_add_f32_dpp v33, v33, v33 row_shr:4 row_mask:0xf bank_mask:0xf bound_ctrl:1
	v_mov_b32_dpp v0, v32 row_bcast:15 row_mask:0xa bank_mask:0xf
	v_add_f32_dpp v34, v34, v34 row_shr:2 row_mask:0xf bank_mask:0xf bound_ctrl:1
	v_add_f32_dpp v33, v33, v33 row_shr:8 row_mask:0xf bank_mask:0xf bound_ctrl:1
	v_add_f32_e32 v65, v32, v0
	v_mov_b32_e32 v0, v2
	v_add_f32_dpp v52, v52, v52 row_shr:1 row_mask:0xf bank_mask:0xf bound_ctrl:1
	v_add_f32_dpp v34, v34, v34 row_shr:4 row_mask:0xf bank_mask:0xf bound_ctrl:1
	v_mov_b32_dpp v0, v33 row_bcast:15 row_mask:0xa bank_mask:0xf
	ds_bpermute_b32 v1, v129, v62
	v_add_f32_dpp v52, v52, v52 row_shr:2 row_mask:0xf bank_mask:0xf bound_ctrl:1
	v_add_f32_dpp v34, v34, v34 row_shr:8 row_mask:0xf bank_mask:0xf bound_ctrl:1
	v_add_f32_e32 v3, v33, v0
	v_mov_b32_e32 v0, v2
	v_add_f32_dpp v52, v52, v52 row_shr:4 row_mask:0xf bank_mask:0xf bound_ctrl:1
	v_cvt_f32_f16_sdwa v35, v35 dst_sel:DWORD dst_unused:UNUSED_PAD src0_sel:WORD_1
	v_mov_b32_dpp v0, v34 row_bcast:15 row_mask:0xa bank_mask:0xf
	v_add_f32_dpp v52, v52, v52 row_shr:8 row_mask:0xf bank_mask:0xf bound_ctrl:1
	v_add_f32_e32 v66, v34, v0
	v_mov_b32_e32 v0, v2
	v_add_f32_dpp v35, v35, v35 row_shr:1 row_mask:0xf bank_mask:0xf bound_ctrl:1
	ds_bpermute_b32 v34, v129, v64
	v_mov_b32_dpp v0, v52 row_bcast:15 row_mask:0xa bank_mask:0xf
	v_add_f32_e32 v67, v52, v0
	s_waitcnt lgkmcnt(1)
	v_sub_f32_e32 v0, v62, v1
	ds_bpermute_b32 v1, v129, v63
	v_add_f32_dpp v35, v35, v35 row_shr:2 row_mask:0xf bank_mask:0xf bound_ctrl:1
	v_med3_f32 v0, v0, s69, v189
	v_mul_f32_e32 v0, 0x3fb8aa3b, v0
	v_add_f32_dpp v35, v35, v35 row_shr:4 row_mask:0xf bank_mask:0xf bound_ctrl:1
	v_exp_f32_e32 v32, v0
	v_mov_b32_e32 v0, v2
	v_add_f32_dpp v35, v35, v35 row_shr:8 row_mask:0xf bank_mask:0xf bound_ctrl:1
	s_waitcnt lgkmcnt(0)
	v_sub_f32_e32 v1, v63, v1
	ds_bpermute_b32 v56, v129, v67
	v_mov_b32_dpp v0, v35 row_bcast:15 row_mask:0xa bank_mask:0xf
	v_med3_f32 v1, v1, s69, v189
	v_add_f32_e32 v68, v35, v0
	v_mul_f32_e32 v1, 0x3fb8aa3b, v1
	v_exp_f32_e32 v33, v1
	ds_bpermute_b32 v1, v129, v65
	ds_bpermute_b32 v54, v129, v3
	ds_bpermute_b32 v55, v129, v66
	ds_bpermute_b32 v57, v129, v68
	s_waitcnt lgkmcnt(4)
	v_sub_f32_e32 v56, v67, v56
	v_med3_f32 v56, v56, s69, v189
	v_mul_f32_e32 v56, 0x3fb8aa3b, v56
	v_sub_f32_e32 v34, v64, v34
	s_waitcnt lgkmcnt(3)
	v_sub_f32_e32 v1, v65, v1
	s_waitcnt lgkmcnt(2)
	v_sub_f32_e32 v54, v3, v54
	s_waitcnt lgkmcnt(1)
	v_sub_f32_e32 v55, v66, v55
	v_exp_f32_e32 v58, v56
	s_waitcnt lgkmcnt(0)
	v_sub_f32_e32 v56, v68, v57
	v_med3_f32 v34, v34, s69, v189
	v_med3_f32 v1, v1, s69, v189
	v_med3_f32 v54, v54, s69, v189
	v_med3_f32 v55, v55, s69, v189
	v_med3_f32 v56, v56, s69, v189
	v_mul_f32_e32 v34, 0x3fb8aa3b, v34
	v_mul_f32_e32 v1, 0x3fb8aa3b, v1
	v_mul_f32_e32 v54, 0x3fb8aa3b, v54
	v_mul_f32_e32 v55, 0x3fb8aa3b, v55
	v_mul_f32_e32 v56, 0x3fb8aa3b, v56
	v_exp_f32_e32 v34, v34
	v_exp_f32_e32 v35, v1
	v_exp_f32_e32 v54, v54
	v_exp_f32_e32 v55, v55
	v_exp_f32_e32 v59, v56
	ds_bpermute_b32 v0, v130, v32
	ds_bpermute_b32 v1, v130, v33
	ds_bpermute_b32 v52, v130, v34
	ds_bpermute_b32 v53, v130, v35
	ds_bpermute_b32 v60, v130, v54
	ds_bpermute_b32 v61, v130, v55
	ds_bpermute_b32 v56, v130, v58
	ds_bpermute_b32 v57, v130, v59
	s_and_saveexec_b64 s[16:17], s[6:7]
	s_cbranch_execz .LBB0_872
	v_mul_f32_e32 v62, 0x3fb8aa3b, v62
	v_mul_f32_e32 v63, 0x3fb8aa3b, v63
	v_mul_f32_e32 v64, 0x3fb8aa3b, v64
	v_mul_f32_e32 v65, 0x3fb8aa3b, v65
	v_exp_f32_e32 v62, v62
	v_exp_f32_e32 v63, v63
	v_exp_f32_e32 v64, v64
	v_exp_f32_e32 v65, v65
	v_mul_f32_e32 v3, 0x3fb8aa3b, v3
	ds_write_b128 v131, v[62:65] offset:34816
	v_exp_f32_e32 v62, v3
	v_mul_f32_e32 v3, 0x3fb8aa3b, v66
	v_exp_f32_e32 v63, v3
	v_mul_f32_e32 v3, 0x3fb8aa3b, v67
	v_exp_f32_e32 v64, v3
	v_mul_f32_e32 v3, 0x3fb8aa3b, v68
	v_exp_f32_e32 v65, v3
	ds_write_b128 v131, v[62:65] offset:34832
.LBB0_872:
	s_or_b64 exec, exec, s[16:17]
	v_rcp_f32_e32 v66, v32
	v_rcp_f32_e32 v67, v33
	s_waitcnt vmcnt(9)
	v_lshlrev_b32_e32 v62, 16, v24
	v_and_b32_e32 v63, 0xffff0000, v24
	v_pk_mul_f32 v[32:33], v[32:33], v[62:63]
	v_lshlrev_b32_e32 v62, 16, v16
	v_and_b32_e32 v63, 0xffff0000, v16
	v_pk_mul_f32 v[62:63], v[66:67], v[62:63]
	v_rcp_f32_e32 v66, v34
	v_rcp_f32_e32 v67, v35
	v_lshlrev_b32_e32 v24, 16, v25
	v_and_b32_e32 v25, 0xffff0000, v25
	v_lshlrev_b32_e32 v16, 16, v17
	v_and_b32_e32 v17, 0xffff0000, v17
	v_pk_mul_f32 v[24:25], v[34:35], v[24:25]
	v_pk_mul_f32 v[34:35], v[66:67], v[16:17]
	v_rcp_f32_e32 v16, v54
	v_rcp_f32_e32 v17, v55
	v_lshlrev_b32_e32 v64, 16, v26
	v_and_b32_e32 v65, 0xffff0000, v26
	v_pk_mul_f32 v[54:55], v[54:55], v[64:65]
	v_lshlrev_b32_e32 v64, 16, v18
	v_and_b32_e32 v65, 0xffff0000, v18
	v_pk_mul_f32 v[64:65], v[16:17], v[64:65]
	v_rcp_f32_e32 v16, v58
	v_rcp_f32_e32 v17, v59
	v_lshlrev_b32_e32 v26, 16, v27
	v_and_b32_e32 v27, 0xffff0000, v27
	v_pk_mul_f32 v[26:27], v[58:59], v[26:27]
	v_lshlrev_b32_e32 v18, 16, v19
	v_and_b32_e32 v19, 0xffff0000, v19
	v_pk_mul_f32 v[58:59], v[16:17], v[18:19]
	v_cvt_pk_bf16_f32 v16, v32, v33
	v_cvt_pk_bf16_f32 v17, v24, v25
	v_cvt_pk_bf16_f32 v18, v54, v55
	v_cvt_pk_bf16_f32 v19, v26, v27
	s_waitcnt lgkmcnt(6)
	v_pk_mul_f32 v[0:1], v[62:63], v[0:1]
	s_waitcnt lgkmcnt(4)
	v_pk_mul_f32 v[52:53], v[34:35], v[52:53]
	s_waitcnt lgkmcnt(2)
	v_pk_mul_f32 v[60:61], v[64:65], v[60:61]
	s_waitcnt lgkmcnt(0)
	v_pk_mul_f32 v[56:57], v[58:59], v[56:57]
	ds_write_b128 v132, v[16:19]
	v_cvt_pk_bf16_f32 v16, v62, v63
	v_cvt_pk_bf16_f32 v17, v34, v35
	v_cvt_pk_bf16_f32 v18, v64, v65
	v_cvt_pk_bf16_f32 v19, v58, v59
	ds_write_b128 v132, v[16:19] offset:8704
	v_cvt_pk_bf16_f32 v16, v0, v1
	v_cvt_pk_bf16_f32 v17, v52, v53
	v_cvt_pk_bf16_f32 v18, v60, v61
	v_cvt_pk_bf16_f32 v19, v56, v57
	ds_write_b128 v132, v[16:19] offset:17408
.LBB0_873:
	s_or_b64 exec, exec, s[80:81]
	s_add_i32 s78, s35, -1
	s_min_i32 s16, s78, s77
	s_lshl_b32 s16, s16, 5
	v_or_b32_e32 v0, s16, v127
	v_xad_u32 v1, v0, -1, s74
	v_cndmask_b32_e64 v0, v1, v0, s[4:5]
	v_add_u32_e32 v1, s16, v128
	v_xad_u32 v3, v1, -1, s74
	v_add_u32_e32 v0, s73, v0
	s_waitcnt vmcnt(8)
	ds_write_b128 v133, v[8:11] offset:26112
	v_cndmask_b32_e64 v3, v3, v1, s[4:5]
	v_ashrrev_i32_e32 v1, 31, v0
	v_mad_i64_i32 v[8:9], s[16:17], v0, s89, v[116:117]
	global_load_dwordx4 v[24:27], v[8:9], off
	v_lshlrev_b64 v[8:9], 10, v[0:1]
	v_lshl_add_u64 v[8:9], v[118:119], 0, v[8:9]
	v_mad_i64_i32 v[0:1], s[16:17], v0, s89, v[120:121]
	global_load_dwordx4 v[32:35], v[8:9], off
	global_load_dwordx4 v[16:19], v[0:1], off
	v_add_u32_e32 v0, s73, v3
	v_mad_i64_i32 v[0:1], s[16:17], v0, s89, v[122:123]
	global_load_dwordx4 v[8:11], v[0:1], off
	v_add_u32_e32 v0, 0x800, v135
	s_waitcnt lgkmcnt(0)
	s_barrier
	ds_read_b64_tr_b16 v[68:69], v134 offset:26112
	ds_read_b64_tr_b16 v[70:71], v134 offset:30464
	ds_read_b64 v[64:65], v135
	ds_read_b64 v[66:67], v135 offset:32
	ds_read_b64 v[52:53], v135 offset:64
	ds_read_b64 v[54:55], v135 offset:96
	ds_read_b64 v[60:61], v0 offset:256
	ds_read_b64 v[62:63], v0 offset:288
	ds_read_b64 v[56:57], v0 offset:320
	ds_read_b64 v[58:59], v0 offset:352
	v_add_u32_e32 v0, 0x2000, v136
	v_add_u32_e32 v1, 0x2800, v136
	ds_read_b64 v[72:73], v0 offset:512
	ds_read_b64 v[74:75], v0 offset:544
	ds_read_b64 v[76:77], v1 offset:768
	ds_read_b64 v[78:79], v1 offset:800
	ds_read_b64 v[84:85], v0 offset:576
	ds_read_b64 v[86:87], v0 offset:608
	ds_read_b64 v[150:151], v1 offset:832
	ds_read_b64 v[152:153], v1 offset:864
	s_waitcnt lgkmcnt(6)
	v_mfma_f32_16x16x32_bf16 v[80:83], v[72:75], v[64:67], 0
	v_mov_b32_e32 v0, s93
	s_waitcnt lgkmcnt(4)
	v_mfma_f32_16x16x32_bf16 v[76:79], v[76:79], v[60:63], 0
	s_waitcnt lgkmcnt(2)
	v_mfma_f32_16x16x32_bf16 v[80:83], v[84:87], v[52:55], v[80:83]
	s_waitcnt lgkmcnt(0)
	v_mfma_f32_16x16x32_bf16 v[76:79], v[150:153], v[56:59], v[76:79]
	v_mov_b32_e32 v150, s93
	s_nop 4
	v_cndmask_b32_e64 v0, v80, v0, s[8:9]
	v_cndmask_b32_e64 v0, v0, v80, s[10:11]
	v_mfma_f32_16x16x32_bf16 v[72:75], v[72:75], v[60:63], 0
	v_cndmask_b32_e64 v3, v82, 0, s[12:13]
	v_cndmask_b32_e64 v1, v76, v150, s[8:9]
	v_cndmask_b32_e64 v76, v1, v76, s[10:11]
	v_cndmask_b32_e64 v1, 0, v81, s[10:11]
	v_cndmask_b32_e64 v80, v83, 0, s[14:15]
	v_mfma_f32_16x16x32_bf16 v[72:75], v[84:87], v[56:59], v[72:75]
	v_cvt_pk_bf16_f32 v0, v0, v1
	v_cvt_pk_bf16_f32 v1, v3, v80
	ds_read_b128 v[80:83], v137 offset:35328
	ds_read_b128 v[84:87], v137 offset:35392
	v_cndmask_b32_e64 v77, 0, v77, s[10:11]
	v_cndmask_b32_e64 v78, v78, 0, s[12:13]
	v_cndmask_b32_e64 v79, v79, 0, s[14:15]
	v_mov_b32_e32 v3, v2
	v_cvt_pk_bf16_f32 v72, v72, v73
	v_cvt_pk_bf16_f32 v73, v74, v75
	v_cvt_pk_bf16_f32 v74, v76, v77
	v_cvt_pk_bf16_f32 v75, v78, v79
	v_mfma_f32_16x16x32_bf16 v[76:79], v[68:71], v[0:3], 0
	s_waitcnt lgkmcnt(1)
	v_pk_mul_f32 v[0:1], v[50:51], v[82:83]
	s_waitcnt lgkmcnt(0)
	v_pk_mul_f32 v[86:87], v[46:47], v[86:87]
	v_pk_mul_f32 v[82:83], v[44:45], v[84:85]
	v_pk_mul_f32 v[80:81], v[48:49], v[80:81]
	v_cvt_pk_bf16_f32 v82, v82, v83
	v_cvt_pk_bf16_f32 v83, v86, v87
	ds_read_b128 v[84:87], v137 offset:35456
	ds_read_b128 v[150:153], v137 offset:35520
	v_cvt_pk_bf16_f32 v80, v80, v81
	v_cvt_pk_bf16_f32 v81, v0, v1
	v_mfma_f32_16x16x32_bf16 v[72:75], v[68:71], v[72:75], 0
	s_waitcnt lgkmcnt(1)
	v_pk_mul_f32 v[0:1], v[42:43], v[86:87]
	s_waitcnt lgkmcnt(0)
	v_pk_mul_f32 v[152:153], v[38:39], v[152:153]
	v_pk_mul_f32 v[86:87], v[36:37], v[150:151]
	v_pk_mul_f32 v[84:85], v[40:41], v[84:85]
	v_cvt_pk_bf16_f32 v86, v86, v87
	v_cvt_pk_bf16_f32 v87, v152, v153
	ds_read_b128 v[150:153], v137 offset:34816
	ds_read_b64_tr_b16 v[156:157], v138 offset:19712
	ds_read_b64_tr_b16 v[154:155], v138 offset:17408
	ds_read_b64_tr_b16 v[158:159], v138 offset:17440
	v_cvt_pk_bf16_f32 v84, v84, v85
	s_waitcnt lgkmcnt(3)
	v_pk_mul_f32 v[50:51], v[50:51], v[152:153]
	v_pk_mul_f32 v[48:49], v[48:49], v[150:151]
	ds_read_b128 v[150:153], v137 offset:34880
	ds_read_b64_tr_b16 v[160:161], v138 offset:19744
	v_cvt_pk_bf16_f32 v85, v0, v1
	v_mfma_f32_16x16x32_bf16 v[64:67], v[80:83], v[64:67], v[76:79]
	v_xor_b32_e32 v1, 0xffffffef, v126
	s_waitcnt lgkmcnt(1)
	v_pk_mul_f32 v[46:47], v[46:47], v[152:153]
	v_pk_mul_f32 v[44:45], v[44:45], v[150:151]
	v_mfma_f32_16x16x32_bf16 v[48:51], v[154:157], v[68:71], v[48:51]
	ds_read_b128 v[150:153], v137 offset:34944
	ds_read_b64_tr_b16 v[154:155], v138 offset:17472
	ds_read_b64_tr_b16 v[156:157], v138 offset:19776
	v_add_u32_e32 v0, 16, v126
	v_cndmask_b32_e64 v3, v149, v126, s[4:5]
	v_mfma_f32_16x16x32_bf16 v[60:63], v[80:83], v[60:63], v[72:75]
	s_waitcnt lgkmcnt(2)
	v_pk_mul_f32 v[42:43], v[42:43], v[152:153]
	v_pk_mul_f32 v[40:41], v[40:41], v[150:151]
	v_add_u32_e32 v1, s74, v1
	v_mfma_f32_16x16x32_bf16 v[52:55], v[84:87], v[52:55], v[64:67]
	s_waitcnt lgkmcnt(0)
	v_mfma_f32_16x16x32_bf16 v[40:43], v[154:157], v[68:71], v[40:43]
	ds_read_b128 v[150:153], v137 offset:35008
	ds_read_b64_tr_b16 v[154:155], v138 offset:17504
	ds_read_b64_tr_b16 v[156:157], v138 offset:19808
	s_waitcnt lgkmcnt(2)
	v_pk_mul_f32 v[38:39], v[38:39], v[152:153]
	v_mfma_f32_16x16x32_bf16 v[56:59], v[84:87], v[56:59], v[60:63]
	v_mul_f32_e64 v36, v36, v150
	v_mul_f32_e64 v37, v37, v151
	s_nop 0
	v_cndmask_b32_e64 v60, v1, v0, s[4:5]
	v_cvt_pk_bf16_f32 v1, v54, v55
	v_add_u32_e32 v54, s73, v3
	v_ashrrev_i32_e32 v55, 31, v54
	v_lshlrev_b64 v[54:55], 11, v[54:55]
	v_cvt_pk_bf16_f32 v0, v52, v53
	v_lshl_add_u64 v[54:55], v[124:125], 0, v[54:55]
	v_mfma_f32_16x16x32_bf16 v[44:47], v[158:161], v[68:71], v[44:47]
	global_store_dwordx2 v[54:55], v[0:1], off offset:1024
	v_add_u32_e32 v0, s73, v60
	v_ashrrev_i32_e32 v1, 31, v0
	s_waitcnt lgkmcnt(0)
	v_mfma_f32_16x16x32_bf16 v[36:39], v[154:157], v[68:71], v[36:39]
	v_lshlrev_b64 v[0:1], 11, v[0:1]
	v_cvt_pk_bf16_f32 v52, v56, v57
	v_cvt_pk_bf16_f32 v53, v58, v59
	v_lshl_add_u64 v[0:1], v[124:125], 0, v[0:1]
	global_store_dwordx2 v[0:1], v[52:53], off offset:1024
	s_and_saveexec_b64 s[80:81], vcc
	s_cbranch_execz .LBB0_868
	s_waitcnt vmcnt(10)
	v_cvt_f32_f16_e32 v0, v28
	v_cvt_f32_f16_sdwa v1, v28 dst_sel:DWORD dst_unused:UNUSED_PAD src0_sel:WORD_1
	v_cvt_f32_f16_e32 v3, v29
	v_cvt_f32_f16_sdwa v28, v29 dst_sel:DWORD dst_unused:UNUSED_PAD src0_sel:WORD_1
	v_add_f32_dpp v0, v0, v0 row_shr:1 row_mask:0xf bank_mask:0xf bound_ctrl:1
	v_add_f32_dpp v1, v1, v1 row_shr:1 row_mask:0xf bank_mask:0xf bound_ctrl:1
	v_mov_b32_e32 v53, v2
	v_add_f32_dpp v0, v0, v0 row_shr:2 row_mask:0xf bank_mask:0xf bound_ctrl:1
	v_add_f32_dpp v1, v1, v1 row_shr:2 row_mask:0xf bank_mask:0xf bound_ctrl:1
	v_cvt_f32_f16_e32 v29, v30
	v_add_f32_dpp v0, v0, v0 row_shr:4 row_mask:0xf bank_mask:0xf bound_ctrl:1
	v_add_f32_dpp v3, v3, v3 row_shr:1 row_mask:0xf bank_mask:0xf bound_ctrl:1
	v_add_f32_dpp v1, v1, v1 row_shr:4 row_mask:0xf bank_mask:0xf bound_ctrl:1
	v_add_f32_dpp v0, v0, v0 row_shr:8 row_mask:0xf bank_mask:0xf bound_ctrl:1
	v_add_f32_dpp v3, v3, v3 row_shr:2 row_mask:0xf bank_mask:0xf bound_ctrl:1
	v_add_f32_dpp v1, v1, v1 row_shr:8 row_mask:0xf bank_mask:0xf bound_ctrl:1
	v_mov_b32_dpp v53, v0 row_bcast:15 row_mask:0xa bank_mask:0xf
	v_add_f32_e32 v62, v0, v53
	v_mov_b32_e32 v0, v2
	v_cvt_f32_f16_sdwa v30, v30 dst_sel:DWORD dst_unused:UNUSED_PAD src0_sel:WORD_1
	v_add_f32_dpp v28, v28, v28 row_shr:1 row_mask:0xf bank_mask:0xf bound_ctrl:1
	v_add_f32_dpp v3, v3, v3 row_shr:4 row_mask:0xf bank_mask:0xf bound_ctrl:1
	v_mov_b32_dpp v0, v1 row_bcast:15 row_mask:0xa bank_mask:0xf
	v_add_f32_dpp v28, v28, v28 row_shr:2 row_mask:0xf bank_mask:0xf bound_ctrl:1
	v_add_f32_dpp v3, v3, v3 row_shr:8 row_mask:0xf bank_mask:0xf bound_ctrl:1
	v_add_f32_e32 v63, v1, v0
	v_mov_b32_e32 v0, v2
	v_cvt_f32_f16_e32 v52, v31
	v_add_f32_dpp v29, v29, v29 row_shr:1 row_mask:0xf bank_mask:0xf bound_ctrl:1
	v_add_f32_dpp v28, v28, v28 row_shr:4 row_mask:0xf bank_mask:0xf bound_ctrl:1
	v_mov_b32_dpp v0, v3 row_bcast:15 row_mask:0xa bank_mask:0xf
	v_add_f32_dpp v29, v29, v29 row_shr:2 row_mask:0xf bank_mask:0xf bound_ctrl:1
	v_add_f32_dpp v28, v28, v28 row_shr:8 row_mask:0xf bank_mask:0xf bound_ctrl:1
	v_add_f32_e32 v64, v3, v0
	v_mov_b32_e32 v0, v2
	v_add_f32_dpp v30, v30, v30 row_shr:1 row_mask:0xf bank_mask:0xf bound_ctrl:1
	v_add_f32_dpp v29, v29, v29 row_shr:4 row_mask:0xf bank_mask:0xf bound_ctrl:1
	v_mov_b32_dpp v0, v28 row_bcast:15 row_mask:0xa bank_mask:0xf
	v_add_f32_dpp v30, v30, v30 row_shr:2 row_mask:0xf bank_mask:0xf bound_ctrl:1
	v_add_f32_dpp v29, v29, v29 row_shr:8 row_mask:0xf bank_mask:0xf bound_ctrl:1
	v_add_f32_e32 v65, v28, v0
	v_mov_b32_e32 v0, v2
	v_add_f32_dpp v52, v52, v52 row_shr:1 row_mask:0xf bank_mask:0xf bound_ctrl:1
	v_add_f32_dpp v30, v30, v30 row_shr:4 row_mask:0xf bank_mask:0xf bound_ctrl:1
	v_mov_b32_dpp v0, v29 row_bcast:15 row_mask:0xa bank_mask:0xf
	ds_bpermute_b32 v1, v129, v62
	v_add_f32_dpp v52, v52, v52 row_shr:2 row_mask:0xf bank_mask:0xf bound_ctrl:1
	v_add_f32_dpp v30, v30, v30 row_shr:8 row_mask:0xf bank_mask:0xf bound_ctrl:1
	v_add_f32_e32 v3, v29, v0
	v_mov_b32_e32 v0, v2
	v_add_f32_dpp v52, v52, v52 row_shr:4 row_mask:0xf bank_mask:0xf bound_ctrl:1
	v_cvt_f32_f16_sdwa v31, v31 dst_sel:DWORD dst_unused:UNUSED_PAD src0_sel:WORD_1
	v_mov_b32_dpp v0, v30 row_bcast:15 row_mask:0xa bank_mask:0xf
	v_add_f32_dpp v52, v52, v52 row_shr:8 row_mask:0xf bank_mask:0xf bound_ctrl:1
	v_add_f32_e32 v66, v30, v0
	v_mov_b32_e32 v0, v2
	v_add_f32_dpp v31, v31, v31 row_shr:1 row_mask:0xf bank_mask:0xf bound_ctrl:1
	ds_bpermute_b32 v30, v129, v64
	v_mov_b32_dpp v0, v52 row_bcast:15 row_mask:0xa bank_mask:0xf
	v_add_f32_e32 v67, v52, v0
	s_waitcnt lgkmcnt(1)
	v_sub_f32_e32 v0, v62, v1
	ds_bpermute_b32 v1, v129, v63
	v_add_f32_dpp v31, v31, v31 row_shr:2 row_mask:0xf bank_mask:0xf bound_ctrl:1
	v_med3_f32 v0, v0, s69, v189
	v_mul_f32_e32 v0, 0x3fb8aa3b, v0
	v_add_f32_dpp v31, v31, v31 row_shr:4 row_mask:0xf bank_mask:0xf bound_ctrl:1
	v_exp_f32_e32 v28, v0
	v_mov_b32_e32 v0, v2
	v_add_f32_dpp v31, v31, v31 row_shr:8 row_mask:0xf bank_mask:0xf bound_ctrl:1
	s_waitcnt lgkmcnt(0)
	v_sub_f32_e32 v1, v63, v1
	ds_bpermute_b32 v56, v129, v67
	v_mov_b32_dpp v0, v31 row_bcast:15 row_mask:0xa bank_mask:0xf
	v_med3_f32 v1, v1, s69, v189
	v_add_f32_e32 v68, v31, v0
	v_mul_f32_e32 v1, 0x3fb8aa3b, v1
	v_exp_f32_e32 v29, v1
	ds_bpermute_b32 v1, v129, v65
	ds_bpermute_b32 v54, v129, v3
	ds_bpermute_b32 v55, v129, v66
	ds_bpermute_b32 v57, v129, v68
	s_waitcnt lgkmcnt(4)
	v_sub_f32_e32 v56, v67, v56
	v_med3_f32 v56, v56, s69, v189
	v_mul_f32_e32 v56, 0x3fb8aa3b, v56
	v_sub_f32_e32 v30, v64, v30
	s_waitcnt lgkmcnt(3)
	v_sub_f32_e32 v1, v65, v1
	s_waitcnt lgkmcnt(2)
	v_sub_f32_e32 v54, v3, v54
	s_waitcnt lgkmcnt(1)
	v_sub_f32_e32 v55, v66, v55
	v_exp_f32_e32 v58, v56
	s_waitcnt lgkmcnt(0)
	v_sub_f32_e32 v56, v68, v57
	v_med3_f32 v30, v30, s69, v189
	v_med3_f32 v1, v1, s69, v189
	v_med3_f32 v54, v54, s69, v189
	v_med3_f32 v55, v55, s69, v189
	v_med3_f32 v56, v56, s69, v189
	v_mul_f32_e32 v30, 0x3fb8aa3b, v30
	v_mul_f32_e32 v1, 0x3fb8aa3b, v1
	v_mul_f32_e32 v54, 0x3fb8aa3b, v54
	v_mul_f32_e32 v55, 0x3fb8aa3b, v55
	v_mul_f32_e32 v56, 0x3fb8aa3b, v56
	v_exp_f32_e32 v30, v30
	v_exp_f32_e32 v31, v1
	v_exp_f32_e32 v54, v54
	v_exp_f32_e32 v55, v55
	v_exp_f32_e32 v59, v56
	ds_bpermute_b32 v0, v130, v28
	ds_bpermute_b32 v1, v130, v29
	ds_bpermute_b32 v52, v130, v30
	ds_bpermute_b32 v53, v130, v31
	ds_bpermute_b32 v60, v130, v54
	ds_bpermute_b32 v61, v130, v55
	ds_bpermute_b32 v56, v130, v58
	ds_bpermute_b32 v57, v130, v59
	s_and_saveexec_b64 s[16:17], s[6:7]
	s_cbranch_execz .LBB0_867
	v_mul_f32_e32 v62, 0x3fb8aa3b, v62
	v_mul_f32_e32 v63, 0x3fb8aa3b, v63
	v_mul_f32_e32 v64, 0x3fb8aa3b, v64
	v_mul_f32_e32 v65, 0x3fb8aa3b, v65
	v_exp_f32_e32 v62, v62
	v_exp_f32_e32 v63, v63
	v_exp_f32_e32 v64, v64
	v_exp_f32_e32 v65, v65
	v_mul_f32_e32 v3, 0x3fb8aa3b, v3
	ds_write_b128 v139, v[62:65]
	v_exp_f32_e32 v62, v3
	v_mul_f32_e32 v3, 0x3fb8aa3b, v66
	v_exp_f32_e32 v63, v3
	v_mul_f32_e32 v3, 0x3fb8aa3b, v67
	v_exp_f32_e32 v64, v3
	v_mul_f32_e32 v3, 0x3fb8aa3b, v68
	v_exp_f32_e32 v65, v3
	ds_write_b128 v139, v[62:65] offset:16
	s_branch .LBB0_867
